# k/v expansion units re-dealt: the sample-prep workgroups take none, workgroups 64..95 take a second unit
# speedup vs baseline: 1.0071x; 1.0060x over previous
; #define PG8_WAIT_V(n) asm volatile("s_waitcnt vmcnt(" #n ")" ::: "memory")
; #define PG8_BAR __builtin_amdgcn_s_barrier()
; template <class Epi, class Sched, bool ALIGN_EPI = false, bool SP2 = false>
; __device__ __forceinline__ void gemm_phase(PG8_LAS unsigned char* lds, const Gemm g, const Sched& S, const Epi& E, const int wave_id  ) {
;     ...
;     for (int i = 0; i < 2; ++i) { int R, C; stage_rc(tid * 16 + i * 8192, R, C); const int Rb = Epi::PERM ? ((R & ~31) + perm32(R & 31)) : R;
;         voffA[i] = (unsigned)(R * K + C) * 2u; voffB[i] = (unsigned)(Rb * K + C) * 2u; }
;     const size_t kstep = (size_t)(BK * 2);
;     const size_t hstep = (size_t)HALF * K * 2;
;     const size_t tstep = 2 * hstep;
;     const unsigned ldsw = (unsigned)wid * 1024u;
;     const int aoff = lds_byte(wr * 64 + fr, fq * 8), boff = lds_byte(wc * 32 + fr, fq * 8);
;     ...
;     Unit cur, nxt; int ui = 0;
;     if (!S.next(0, cur)) return;
;     f32x4 acc[2][2][4][2];
; #pragma unroll
;     for (int a = 0; a < 2; ++a)
; #pragma unroll
;         for (int b = 0; b < 2; ++b)
; #pragma unroll
;             for (int m = 0; m < 4; ++m)
; #pragma unroll
;                 for (int n = 0; n < 2; ++n) acc[a][b][m][n] = (f32x4){0.f, 0.f, 0.f, 0.f};
;     bf16x8 At[4][2], B0[2][2], B1[2][2];
;     const char* cA = (const char*)g.A + (size_t)cur.pm * tstep; const char* cB = (const char*)g.Bt + (size_t)cur.pn * tstep;
;     S.a_ready(cur);
;     if constexpr (SP2) {
;         PG8_STAGE(PG8_SB(0, 0), cB, voffB); PG8_STAGE(PG8_SB(0, 1), cB + hstep, voffB); PG8_STAGE(PG8_SA(0, 0), cA, voffA); PG8_STAGE(PG8_SA(0, 1), cA + hstep, voffA);
;         if (wr == 1) PG8_BAR;
;         PG8_WAIT_V(2); PG8_BAR;
;         PG8_STAGE(PG8_SB(1, 0), cB + kstep, voffB); PG8_STAGE(PG8_SA(1, 0), cA + kstep, voffA); PG8_STAGE(PG8_SB(1, 1), cB + hstep + kstep, voffB);
;         PG8_WAIT_V(6); PG8_BAR;
;     } else {
;         PG8_STAGE(PG8_SB(0, 0), cB, voffB); PG8_STAGE(PG8_SA(0, 0), cA, voffA); PG8_STAGE(PG8_SB(0, 1), cB + hstep, voffB); PG8_STAGE(PG8_SA(0, 1), cA + hstep, voffA);
;         if (wr == 1) PG8_BAR;
;         PG8_WAIT_V(4); PG8_BAR;
;         PG8_STAGE(PG8_SB(1, 0), cB + kstep, voffB); PG8_STAGE(PG8_SA(1, 0), cA + kstep, voffA); PG8_STAGE(PG8_SB(1, 1), cB + hstep + kstep, voffB);
;         PG8_WAIT_V(6); PG8_BAR;
;     }
;     for (;;) {
;         const bool has_next = S.next(ui + 1, nxt);
.LBB0_849:
	v_readlane_b32 s1, v254, 3
	v_mbcnt_lo_u32_b32 v0, -1, 0
	v_mbcnt_hi_u32_b32 v0, -1, v0
	s_nop 1
	v_add_u32_e32 v10, s1, v0
	v_readlane_b32 s1, v254, 58
	s_cmpk_gt_i32 s1, 0xdf
	v_readfirstlane_b32 s4, v10
	s_cbranch_scc1 .LBB0_867
	v_lshlrev_b32_e32 v0, 4, v10
	v_add_u32_e32 v2, 0x2000, v0
	v_ashrrev_i32_e32 v3, 31, v2
	v_lshrrev_b32_e32 v3, 22, v3
	v_add_u32_e32 v3, v2, v3
	v_ashrrev_i32_e32 v3, 10, v3
	v_mul_i32_i24_e32 v4, 0x400, v3
	v_sub_u32_e32 v2, v2, v4
	v_lshrrev_b32_e32 v4, 4, v2
	v_bitop3_b32 v2, v4, v2, 32 bitop3:0x6c
	v_ashrrev_i32_e32 v4, 31, v2
	v_lshrrev_b32_e32 v4, 26, v4
	v_add_u32_e32 v4, v2, v4
	v_lshlrev_b32_e32 v6, 3, v3
	v_ashrrev_i32_e32 v5, 6, v4
	v_and_b32_e32 v6, -16, v6
	v_and_b32_e32 v4, 0xc0, v4
	v_add_u32_e32 v6, v5, v6
	v_sub_u32_e32 v2, v2, v4
	v_and_b32_e32 v5, 3, v5
	s_mov_b32 s1, 0x7fffe0
	v_lshrrev_b32_e32 v7, 2, v6
	v_lshlrev_b32_e32 v8, 1, v6
	v_lshlrev_b32_e32 v3, 5, v3
	v_ashrrev_i16_sdwa v2, v221, sext(v2) dst_sel:DWORD dst_unused:UNUSED_PAD src0_sel:DWORD src1_sel:BYTE_0
	v_and_or_b32 v5, v6, s1, v5
	v_and_b32_e32 v7, 4, v7
	v_and_b32_e32 v8, 24, v8
	v_and_b32_e32 v3, 32, v3
	v_bfe_i32 v2, v2, 0, 16
	v_or3_b32 v5, v5, v7, v8
	v_add_lshl_u32 v2, v3, v2, 1
	v_lshl_add_u32 v130, v5, 9, v2
	v_lshl_add_u32 v132, v6, 9, v2
	v_bfe_i32 v2, v10, 27, 1
	v_lshrrev_b32_e32 v2, 22, v2
	v_add_u32_e32 v2, v0, v2
	v_and_b32_e32 v2, 0xfffffc00, v2
	v_sub_u32_e32 v0, v0, v2
	v_lshrrev_b32_e32 v2, 4, v0
	v_ashrrev_i32_e32 v4, 31, v10
	v_bitop3_b32 v0, v2, v0, 32 bitop3:0x6c
	v_lshrrev_b32_e32 v4, 26, v4
	v_ashrrev_i32_e32 v2, 31, v0
	v_add_u32_e32 v4, v10, v4
	s_add_u32 s37, s26, 0xbe18100
	v_lshrrev_b32_e32 v2, 26, v2
	v_ashrrev_i32_e32 v4, 6, v4
	s_addc_u32 s44, s27, 0
	v_add_u32_e32 v2, v0, v2
	v_lshlrev_b32_e32 v5, 3, v4
	s_mov_b32 s88, s34
	s_add_u32 s34, s97, 0x360000
	v_ashrrev_i32_e32 v3, 6, v2
	v_and_b32_e32 v5, -16, v5
	v_readlane_b32 s6, v254, 58
	s_addc_u32 s35, s7, 0
	v_add_u32_e32 v5, v3, v5
	v_and_b32_e32 v3, 3, v3
	s_lshl_b32 s6, s6, 5
	v_and_or_b32 v3, v5, s1, v3
	s_lshr_b32 s1, s33, 3
	s_and_b32 s6, s6, 0xe0
	s_add_i32 s6, s6, s1
	s_lshr_b32 s1, s6, 2
	s_and_b32 s1, s1, 0xffffff8
	s_bfe_u32 s6, s33, 0x30003
	s_ashr_i32 s14, s4, 6
	s_or_b32 s56, s1, s6
	s_bfe_u32 s12, s33, 0x20006
	s_ashr_i32 s15, s4, 8
	s_lshl_b32 s5, s14, 10
	s_lshl_b64 s[6:7], s[56:57], 17
	s_lshl_b32 s1, s12, 17
	s_add_u32 s38, s34, s1
	s_addc_u32 s39, s35, 0
	s_add_i32 s45, s96, 0x10000
	v_and_b32_e32 v2, 0xc0, v2
	s_add_i32 s46, s45, s5
	v_sub_u32_e32 v0, v0, v2
	s_add_i32 s47, s46, 0x2000
	v_lshrrev_b32_e32 v6, 2, v5
	v_lshlrev_b32_e32 v7, 1, v5
	v_lshlrev_b32_e32 v4, 5, v4
	v_ashrrev_i16_sdwa v0, v221, sext(v0) dst_sel:DWORD dst_unused:UNUSED_PAD src0_sel:DWORD src1_sel:BYTE_0
	s_add_u32 s10, s38, 0x10000
	v_and_b32_e32 v6, 4, v6
	v_and_b32_e32 v7, 24, v7
	v_and_b32_e32 v4, 32, v4
	v_bfe_i32 v0, v0, 0, 16
	s_addc_u32 s11, s39, 0
	s_add_i32 s48, s96, 0x14000
	v_or3_b32 v3, v3, v6, v7
	v_add_lshl_u32 v2, v4, v0, 1
	s_add_i32 s49, s48, s5
	v_lshl_add_u32 v0, v3, 9, v2
	s_mov_b32 m0, s46
	s_add_i32 s50, s49, 0x2000
	global_load_lds_dwordx4 v0, s[38:39]
	s_mov_b32 m0, s47
	s_add_u32 s6, s37, s6
	global_load_lds_dwordx4 v130, s[38:39]
	s_mov_b32 m0, s49
	s_addc_u32 s7, s44, s7
	s_add_i32 s51, s96, s5
	global_load_lds_dwordx4 v0, s[10:11]
	s_mov_b32 m0, s50
	s_add_i32 s52, s51, 0x2000
	v_lshl_add_u32 v134, v5, 9, v2
	global_load_lds_dwordx4 v130, s[10:11]
	s_mov_b32 m0, s51
	s_add_u32 s10, s6, 0x10000
	global_load_lds_dwordx4 v134, s[6:7]
	s_mov_b32 m0, s52
	s_addc_u32 s11, s7, 0
	s_add_i32 s53, s51, 0x4000
	global_load_lds_dwordx4 v132, s[6:7]
	s_mov_b32 m0, s53
	s_add_i32 s54, s51, 0x6000
	global_load_lds_dwordx4 v134, s[10:11]
	s_mov_b32 m0, s54
	v_mov_b32_e32 v131, v1
	global_load_lds_dwordx4 v132, s[10:11]
	v_mov_b32_e32 v135, v1
	v_mov_b32_e32 v133, v1
	s_cmp_eq_u32 s15, 1
	v_lshl_add_u64 v[8:9], s[38:39], 0, v[0:1]
	v_lshl_add_u64 v[6:7], s[38:39], 0, v[130:131]
	v_lshl_add_u64 v[2:3], s[6:7], 0, v[134:135]
	s_cselect_b64 s[10:11], -1, 0
	s_cmp_lg_u32 s15, 1
	v_lshl_add_u64 v[4:5], s[6:7], 0, v[132:133]
	s_cbranch_scc1 .LBB0_852
	s_barrier
.LBB0_852:
	s_and_b32 s72, 0xffff, s12
	s_add_u32 s12, s26, 0xc618100
	s_addc_u32 s13, s27, 0
	s_lshl_b32 s55, s15, 6
	v_and_b32_e32 v11, 48, v10
	s_lshl_b32 s1, s15, 13
	v_lshlrev_b32_e32 v12, 6, v10
	s_movk_i32 s15, 0x3c0
	v_lshlrev_b32_e32 v10, 2, v10
	v_and_or_b32 v11, v12, s15, v11
	v_and_b32_e32 v10, 32, v10
	v_bitop3_b32 v12, v11, s1, v10 bitop3:0xde
	s_lshl_b32 s1, s14, 5
	s_add_i32 s59, s96, 0x18000
	s_and_b32 s58, s1, 0x60
	s_add_i32 s60, s59, s5
	s_lshl_b32 s1, s58, 7
	v_lshl_add_u64 v[8:9], v[8:9], 0, s[66:67]
	s_mov_b32 m0, s60
	s_add_i32 s61, s60, 0x2000
	s_add_i32 s62, s51, 0x8000
	s_add_i32 s63, s51, 0xa000
	s_waitcnt vmcnt(2)
	s_barrier
	global_load_lds_dwordx4 v[8:9], off
	v_lshl_add_u64 v[6:7], v[6:7], 0, s[66:67]
	s_mov_b32 m0, s61
	s_add_u32 s14, s38, 0x10080
	global_load_lds_dwordx4 v[6:7], off
	v_lshl_add_u64 v[2:3], v[2:3], 0, s[66:67]
	s_mov_b32 m0, s62
	s_addc_u32 s15, s39, 0
	s_add_i32 s64, s96, 0x1c000
	global_load_lds_dwordx4 v[2:3], off
	v_lshl_add_u64 v[2:3], v[4:5], 0, s[66:67]
	s_mov_b32 m0, s63
	s_add_i32 s65, s64, s5
	global_load_lds_dwordx4 v[2:3], off
	v_lshl_add_u64 v[2:3], s[14:15], 0, v[0:1]
	s_mov_b32 m0, s65
	s_add_i32 s70, s65, 0x2000
	global_load_lds_dwordx4 v[2:3], off
	v_lshl_add_u64 v[2:3], s[14:15], 0, v[130:131]
	s_mov_b32 m0, s70
	s_cmpk_lt_u32 s4, 0x100
	global_load_lds_dwordx4 v[2:3], off
	s_waitcnt vmcnt(6)
	s_cselect_b64 s[14:15], -1, 0
	s_ashr_i32 s71, s36, 31
	s_add_u32 s16, s36, s33
	v_bitop3_b32 v144, s1, v11, v10 bitop3:0xf6
	s_addc_u32 s17, s71, 0
	s_cmpk_lt_u32 s33, 32
	s_cbranch_scc1 .Lkv_keep
	s_cmpk_gt_u32 s33, 63
	s_cbranch_scc1 .Lkv_keep
	s_add_u32 s16, s33, 0xa0
	s_mov_b32 s17, 0
.Lkv_keep:
	v_add_u32_e32 v145, s96, v12
	s_barrier
	s_branch .LBB0_855
